# attention unit order remapped so each XCD reads the Q/K/Z rows its own workgroups wrote in the previous phase (L2 locality experiment)
# speedup vs baseline: 1.0056x; 1.0045x over previous
; #define LAS __attribute__((address_space(3)))
; __device__ __forceinline__ void attn_phase(LAS unsigned char* lds, const bf16_t* Q, const bf16_t* Kb, const bf16_t* VT, const bf16_t* Zs, bf16_t* OZ, int vcu, int G) {
;     const int tid = threadIdx.x, lane = tid & 63, w = __builtin_amdgcn_readfirstlane(tid >> 6), ql = lane & 31, hi = lane >> 5;
;     constexpr float STOP = 5.421010862427522e-20f;
;     LAS unsigned char* KL = lds;
;     LAS unsigned char* VL = lds + 49152;
;     constexpr int NU = BATCH * 16 * (SEQ / 256);
;     u32x4 sk[6], sv[6];
;     ...
;     if (vcu < NU) ATT_LOAD_STAGE(vcu);
.LBB0_536:
	s_cmp_lt_i32 s54, 8
	s_cselect_b64 s[4:5], -1, 0
	s_and_b64 s[70:71], s[4:5], s[0:1]
	s_andn2_b64 vcc, exec, s[70:71]
	s_cbranch_vccnz .LBB0_557
	s_cmpk_gt_i32 s84, 0x3ff
	v_readfirstlane_b32 s0, v0
	s_cbranch_scc1 .LBB0_557
	s_mov_b32 s98, 0x42fc0000
	s_lshr_b32 s85, s0, 6
	s_and_b32 s100, s84, 7
	s_bfe_u32 s99, s84, 0x20005
	s_lshl_b32 s99, s99, 3
	s_or_b32 s100, s100, s99
	s_bfe_u32 s99, s84, 0x20003
	s_lshl_b32 s99, s99, 5
	s_or_b32 s100, s100, s99
	s_bfe_u32 s99, s84, 0x20008
	s_lshl_b32 s99, s99, 7
	s_or_b32 s100, s100, s99
	s_bfe_u32 s99, s84, 0x10007
	s_lshl_b32 s99, s99, 9
	s_or_b32 s100, s100, s99
	s_ashr_i32 s0, s100, 9
	s_lshl_b32 s8, s100, 8
	s_ashr_i32 s1, s0, 31
	s_and_b32 s8, s8, 0x1f00
	s_bfe_u32 s14, s100, 0x40005
	s_lshl_b64 s[4:5], s[0:1], 13
	s_add_i32 s9, s8, 0xffffff80
	s_cmp_lg_u32 s8, 0
	s_cselect_b32 s8, s9, 0
	s_ashr_i32 s9, s8, 31
	s_add_u32 s10, s4, s8
	s_addc_u32 s11, s5, s9
	s_lshl_b32 s4, s14, 7
	v_lshrrev_b32_e32 v146, 3, v0
	s_waitcnt vmcnt(0)
	v_or_b32_e32 v9, 0x200, v0
	s_add_u32 s12, s6, s4
	v_lshlrev_b32_e32 v8, 4, v0
	v_or_b32_e32 v4, s10, v146
	v_mov_b32_e32 v5, s11
	v_lshrrev_b32_e32 v148, 3, v9
	s_addc_u32 s13, s7, 0
	v_and_b32_e32 v144, 0x70, v8
	v_mov_b32_e32 v145, 0
	v_lshlrev_b64 v[6:7], 11, v[4:5]
	v_or_b32_e32 v4, s10, v148
	s_waitcnt lgkmcnt(0)
	v_lshl_add_u64 v[2:3], s[12:13], 0, v[144:145]
	v_lshlrev_b64 v[4:5], 11, v[4:5]
	v_or_b32_e32 v10, 0x400, v0
	v_or_b32_e32 v11, 0x600, v0
	v_lshl_add_u64 v[6:7], v[2:3], 0, v[6:7]
	v_lshl_add_u64 v[4:5], v[2:3], 0, v[4:5]
	v_lshrrev_b32_e32 v150, 3, v10
	v_mov_b32_e32 v151, v145
	v_lshrrev_b32_e32 v152, 3, v11
	v_mov_b32_e32 v153, v145
	global_load_dwordx4 v[66:69], v[6:7], off
	global_load_dwordx4 v[70:73], v[4:5], off
	v_lshl_add_u64 v[4:5], s[10:11], 0, v[150:151]
	v_lshl_add_u64 v[6:7], s[10:11], 0, v[152:153]
	v_lshlrev_b64 v[4:5], 11, v[4:5]
	v_lshlrev_b64 v[6:7], 11, v[6:7]
	v_or_b32_e32 v12, 0x800, v0
	v_or_b32_e32 v13, 0xa00, v0
	v_lshl_add_u64 v[4:5], v[2:3], 0, v[4:5]
	v_lshl_add_u64 v[6:7], v[2:3], 0, v[6:7]
	v_lshrrev_b32_e32 v154, 3, v12
	v_mov_b32_e32 v155, v145
	v_lshrrev_b32_e32 v156, 3, v13
	v_mov_b32_e32 v157, v145
	global_load_dwordx4 v[74:77], v[4:5], off
	global_load_dwordx4 v[78:81], v[6:7], off
	v_lshl_add_u64 v[4:5], s[10:11], 0, v[154:155]
	v_lshl_add_u64 v[6:7], s[10:11], 0, v[156:157]
	v_lshlrev_b64 v[4:5], 11, v[4:5]
	v_lshlrev_b64 v[6:7], 11, v[6:7]
	v_lshl_add_u64 v[4:5], v[2:3], 0, v[4:5]
	v_lshl_add_u64 v[2:3], v[2:3], 0, v[6:7]
	s_lshl_b64 s[0:1], s[0:1], 14
	global_load_dwordx4 v[82:85], v[4:5], off
	global_load_dwordx4 v[86:89], v[2:3], off
	s_add_u32 s5, s68, s0
	v_mul_u32_u24_e32 v2, 0x556, v0
	s_addc_u32 s10, s69, s1
	s_lshl_b64 s[0:1], s[8:9], 1
	v_lshrrev_b32_e32 v2, 16, v2
	s_add_u32 s0, s5, s0
	v_mul_lo_u16_e32 v3, 48, v2
	s_addc_u32 s1, s10, s1
	v_sub_u16_e32 v4, v0, v3
	s_lshl_b32 s5, s14, 21
	v_lshl_or_b32 v2, v2, 15, s5
	v_mov_b32_e32 v3, v145
	v_lshlrev_b16_e32 v4, 3, v4
	v_lshl_add_u64 v[2:3], s[0:1], 0, v[2:3]
	v_lshlrev_b32_e32 v4, 1, v4
	v_mov_b32_e32 v5, v145
	v_lshl_add_u64 v[2:3], v[2:3], 0, v[4:5]
	v_mul_u32_u24_e32 v4, 0x556, v9
	v_lshrrev_b32_e32 v4, 16, v4
	v_mul_lo_u16_e32 v5, 48, v4
	v_sub_u16_e32 v6, v9, v5
	v_lshl_or_b32 v4, v4, 15, s5
	v_mov_b32_e32 v5, v145
	v_lshlrev_b16_e32 v6, 3, v6
	v_lshl_add_u64 v[4:5], s[0:1], 0, v[4:5]
	v_lshlrev_b32_e32 v6, 1, v6
	v_mov_b32_e32 v7, v145
	v_lshl_add_u64 v[4:5], v[4:5], 0, v[6:7]
	global_load_dwordx4 v[94:97], v[2:3], off
	global_load_dwordx4 v[90:93], v[4:5], off
	v_mul_u32_u24_e32 v2, 0x556, v10
	v_lshrrev_b32_e32 v2, 16, v2
	v_mul_lo_u16_e32 v3, 48, v2
	v_sub_u16_e32 v4, v10, v3
	v_lshl_or_b32 v2, v2, 15, s5
	v_mov_b32_e32 v3, v145
	v_lshlrev_b16_e32 v4, 3, v4
	v_lshl_add_u64 v[2:3], s[0:1], 0, v[2:3]
	v_lshlrev_b32_e32 v4, 1, v4
	v_mov_b32_e32 v5, v145
	v_lshl_add_u64 v[2:3], v[2:3], 0, v[4:5]
	v_mul_u32_u24_e32 v4, 0x556, v11
	v_lshrrev_b32_e32 v4, 16, v4
	v_mul_lo_u16_e32 v5, 48, v4
	v_sub_u16_e32 v6, v11, v5
	v_lshl_or_b32 v4, v4, 15, s5
	v_mov_b32_e32 v5, v145
	v_lshlrev_b16_e32 v6, 3, v6
	v_lshl_add_u64 v[4:5], s[0:1], 0, v[4:5]
	v_lshlrev_b32_e32 v6, 1, v6
	v_lshl_add_u64 v[4:5], v[4:5], 0, v[6:7]
	global_load_dwordx4 v[102:105], v[2:3], off
	global_load_dwordx4 v[98:101], v[4:5], off
	v_mul_u32_u24_e32 v2, 0xaab, v12
	v_lshrrev_b32_e32 v2, 17, v2
	v_mul_lo_u16_e32 v3, 48, v2
	v_sub_u16_e32 v4, v12, v3
	v_lshl_or_b32 v2, v2, 15, s5
	v_mov_b32_e32 v3, v145
	v_lshlrev_b16_e32 v4, 3, v4
	v_lshl_add_u64 v[2:3], s[0:1], 0, v[2:3]
	v_lshlrev_b32_e32 v4, 1, v4
	v_mov_b32_e32 v5, v145
	v_lshl_add_u64 v[2:3], v[2:3], 0, v[4:5]
	v_mul_u32_u24_e32 v4, 0xaab, v13
	v_lshrrev_b32_e32 v4, 17, v4
	v_mul_lo_u16_e32 v5, 48, v4
	v_sub_u16_e32 v6, v13, v5
	v_lshl_or_b32 v4, v4, 15, s5
	v_mov_b32_e32 v5, v145
	v_lshlrev_b16_e32 v6, 3, v6
	v_lshl_add_u64 v[4:5], s[0:1], 0, v[4:5]
	v_lshlrev_b32_e32 v6, 1, v6
	v_lshl_add_u64 v[4:5], v[4:5], 0, v[6:7]
; #define LAS __attribute__((address_space(3)))
; __device__ __forceinline__ void attn_phase(LAS unsigned char* lds, const bf16_t* Q, const bf16_t* Kb, const bf16_t* VT, const bf16_t* Zs, bf16_t* OZ, int vcu, int G) {
;     ...
;     u32x4 sk[6], sv[6];
;     ...
;     if (vcu < NU) ATT_LOAD_STAGE(vcu);
;     for (int unit = vcu; unit < NU; unit += G) {
;         ATT_DECODE(unit, h, rowbase, q0b, kw0)
;         const int qblk = unit & 31;
;         const int qb = 8 * qblk + w, q0 = 32 * qb;
;         bf16x8 qf[4];
;         { const bf16_t* qp = Q + (rowbase + q0 + ql) * D + h * 64 + 8 * hi;
; #pragma unroll
;           for (int kk = 0; kk < 4; ++kk) qf[kk] = *(const bf16x8*)(qp + 16 * kk); }
;         u32x2 zz[8];
;         { const bf16_t* zp = Zs + (rowbase + q0 + ql) * D + h * 64 + 4 * hi;
; #pragma unroll
;           for (int g4 = 0; g4 < 4; ++g4) { zz[g4] = *(const u32x2*)(zp + 8 * g4); zz[4 + g4] = *(const u32x2*)(zp + 32 + 8 * g4); } }
;         asm volatile("" ::: "memory");
; #pragma unroll
;         for (int i = 0; i < 6; ++i) { const int idx = tid + NTHR * i, r = idx >> 3, c = idx & 7;
;             *(LAS u32x4*)(KL + r * 128 + ((c ^ ((r >> 1) & 7)) << 4)) = sk[i]; }
; #pragma unroll
;         for (int i = 0; i < 6; ++i) { const int idx = tid + NTHR * i, d = idx / 48, ch = idx % 48;
;             { u32x4 v = sv[i]; const int gp = (2 * ch) ^ (d & 31);
;                 if (d & 1) { const u32x4 t = v; v.x = t.z; v.y = t.w; v.z = t.x; v.w = t.y; }
;                 *(LAS u32x4*)(VL + d * 768 + ((gp & ~1) << 3)) = v; } }
	global_load_dwordx4 v[110:113], v[2:3], off
	global_load_dwordx4 v[106:109], v[4:5], off
	s_movk_i32 s5, 0x3f80
	v_mov_b32_e32 v6, 0x2000
	v_bitop3_b32 v7, v8, s5, v6 bitop3:0xc8
	s_movk_i32 s5, 0x7f80
	v_mov_b32_e32 v6, 0x6000
	v_bitop3_b32 v15, v8, s5, v6 bitop3:0xc8
	s_mov_b32 s5, 0xbf80
	v_mov_b32_e32 v6, 0xa000
	s_mov_b32 s12, 0x5555556
	s_movk_i32 s4, 0x70
	v_bitop3_b32 v17, v8, s5, v6 bitop3:0xc8
	v_mul_hi_u32 v6, v0, s12
	v_bitop3_b32 v3, v8, s4, v0 bitop3:0x48
	v_and_b32_e32 v5, 0x1f80, v8
	v_mul_u32_u24_e32 v8, 48, v6
	v_sub_u32_e32 v8, v0, v8
	v_and_b32_e32 v14, 1, v6
	v_cmp_eq_u32_e64 s[48:49], 0, v14
	v_lshlrev_b32_e32 v14, 4, v8
	v_lshlrev_b32_e32 v16, 3, v6
	v_bitop3_b32 v19, v16, v14, s4 bitop3:0x6c
	v_mul_hi_u32 v14, v9, s12
	v_mul_u32_u24_e32 v16, 48, v14
	v_bfe_u32 v1, v0, 5, 1
	v_sub_u32_e32 v9, v9, v16
	v_and_b32_e32 v16, 1, v14
	v_lshlrev_b32_e32 v4, 2, v1
	s_movk_i32 s14, 0x300
	v_cmp_eq_u32_e64 s[4:5], 0, v16
	v_lshlrev_b32_e32 v16, 4, v9
	v_lshlrev_b32_e32 v21, 3, v14
	s_movk_i32 s15, 0xf0
	v_and_b32_e32 v142, 31, v0
	v_mad_u32_u24 v18, v6, s14, 0
	v_bitop3_b32 v21, v21, v16, s15 bitop3:0x6c
	v_mul_hi_u32 v16, v10, s12
	v_lshlrev_b32_e32 v196, 14, v6
	v_lshlrev_b32_e32 v6, 3, v8
	v_lshlrev_b32_e32 v8, 3, v9
	v_or_b32_e32 v9, 1, v4
	v_mul_u32_u24_e32 v22, 48, v16
	v_cmp_lt_u32_e64 s[16:17], v9, v142
	v_or_b32_e32 v9, 2, v4
	v_sub_u32_e32 v10, v10, v22
	v_cmp_lt_u32_e64 s[18:19], v9, v142
	v_or_b32_e32 v9, 3, v4
	v_lshlrev_b32_e32 v23, 4, v10
	v_lshlrev_b32_e32 v24, 3, v16
	v_cmp_lt_u32_e64 s[20:21], v9, v142
	v_or_b32_e32 v9, 8, v4
	v_bitop3_b32 v23, v24, v23, s15 bitop3:0x6c
	v_mul_hi_u32 v24, v11, s12
	v_cmp_lt_u32_e64 s[22:23], v9, v142
	v_or_b32_e32 v9, 9, v4
	v_mul_u32_u24_e32 v25, 48, v24
	v_cmp_lt_u32_e64 s[24:25], v9, v142
	v_or_b32_e32 v9, 10, v4
	v_sub_u32_e32 v11, v11, v25
	v_cmp_lt_u32_e64 s[26:27], v9, v142
	v_or_b32_e32 v9, 11, v4
	v_lshlrev_b32_e32 v26, 4, v11
	v_lshlrev_b32_e32 v27, 3, v24
	v_cmp_lt_u32_e64 s[28:29], v9, v142
	v_or_b32_e32 v9, 16, v4
	v_bitop3_b32 v26, v27, v26, s15 bitop3:0x6c
	v_mul_hi_u32 v27, v12, s12
	v_cmp_lt_u32_e64 s[30:31], v9, v142
	v_or_b32_e32 v9, 17, v4
	v_mul_u32_u24_e32 v28, 48, v27
	v_cmp_lt_u32_e64 s[34:35], v9, v142
	v_or_b32_e32 v9, 18, v4
	v_sub_u32_e32 v28, v12, v28
	v_and_b32_e32 v12, 1, v27
	v_cmp_lt_u32_e64 s[36:37], v9, v142
	v_or_b32_e32 v9, 19, v4
	v_cmp_eq_u32_e64 s[10:11], 0, v12
	v_lshlrev_b32_e32 v12, 4, v28
	v_lshlrev_b32_e32 v30, 3, v27
	v_mul_hi_u32 v31, v13, s12
	v_cmp_lt_u32_e64 s[38:39], v9, v142
	v_or_b32_e32 v9, 24, v4
	v_bitop3_b32 v30, v30, v12, s15 bitop3:0x6c
	v_mul_u32_u24_e32 v12, 48, v31
	v_cmp_lt_u32_e64 s[40:41], v9, v142
	v_or_b32_e32 v9, 25, v4
	v_sub_u32_e32 v13, v13, v12
	v_and_b32_e32 v12, 1, v31
	v_cmp_lt_u32_e64 s[42:43], v9, v142
	v_or_b32_e32 v9, 26, v4
	s_lshl_b32 s58, s85, 12
	v_lshlrev_b32_e32 v2, 3, v1
	v_lshl_add_u64 v[158:159], s[6:7], 0, v[144:145]
	v_lshlrev_b32_e32 v144, 4, v1
	v_and_b32_e32 v22, 1, v16
	v_and_b32_e32 v25, 1, v24
	v_cmp_eq_u32_e64 s[12:13], 0, v12
	v_lshlrev_b32_e32 v12, 4, v13
	v_lshlrev_b32_e32 v33, 3, v31
	v_cmp_lt_u32_e64 s[44:45], v9, v142
	v_or_b32_e32 v9, 27, v4
	s_add_i32 s58, s58, 0
	v_add_u32_e32 v3, 0, v3
	v_lshl_add_u64 v[160:161], s[6:7], 0, v[144:145]
	v_mad_u32_u24 v20, v14, s14, 0
	v_cmp_eq_u32_e64 s[6:7], 0, v22
	v_mad_u32_u24 v22, v16, s14, 0
	v_cmp_eq_u32_e64 s[8:9], 0, v25
	v_mad_u32_u24 v25, v24, s14, 0
	v_mad_u32_u24 v29, v27, s14, 0
	v_mad_u32_u24 v32, v31, s14, 0
	v_bitop3_b32 v33, v33, v12, s15 bitop3:0x6c
	v_lshlrev_b32_e32 v197, 14, v14
	v_lshlrev_b32_e32 v198, 14, v16
	v_lshlrev_b32_e32 v10, 3, v10
	v_lshlrev_b32_e32 v12, 3, v11
	v_lshlrev_b32_e32 v14, 3, v28
	v_lshlrev_b32_e32 v16, 3, v13
	v_mad_u32_u24 v202, v142, s14, 0
	v_cmp_lt_u32_e64 s[46:47], v9, v142
	v_lshl_add_u32 v9, v142, 7, s58
	v_lshlrev_b32_e32 v144, 1, v2
	v_mbcnt_lo_u32_b32 v2, -1, 0
	s_mov_b32 s73, 0
	v_or_b32_e32 v143, 2, v1
	v_or_b32_e32 v147, 4, v1
	v_or_b32_e32 v149, 6, v1
	v_cmp_eq_u32_e64 s[0:1], 0, v1
	v_lshlrev_b32_e32 v199, 14, v24
	v_lshlrev_b32_e32 v200, 14, v27
	v_lshlrev_b32_e32 v201, 14, v31
	v_add_u32_e32 v203, 0xc000, v202
	v_cmp_lt_u32_e64 s[14:15], v4, v142
	s_add_i32 s86, s85, 1
	s_lshl_b32 s87, s85, 5
	v_or_b32_e32 v204, 0xffffffe0, v142
	v_add_u32_e32 v205, 0xfffff000, v9
	v_lshlrev_b32_e32 v162, 1, v4
	v_add_u32_e32 v206, v3, v5
	v_add_u32_e32 v207, v3, v7
	v_add_u32_e32 v208, v3, v15
	v_add_u32_e32 v209, v3, v17
	v_add_u32_e32 v210, v18, v19
	v_add_u32_e32 v211, v20, v21
	v_add_u32_e32 v212, v22, v23
	v_add_u32_e32 v213, v25, v26
	v_add_u32_e32 v214, v29, v30
	v_add_u32_e32 v215, v32, v33
	v_lshlrev_b32_e32 v164, 1, v6
	v_lshlrev_b32_e32 v166, 1, v8
	v_lshlrev_b32_e32 v168, 1, v10
	v_lshlrev_b32_e32 v170, 1, v12
	v_lshlrev_b32_e32 v172, 1, v14
	v_lshlrev_b32_e32 v174, 1, v16
	s_mov_b32 s88, 0x1f800000
	v_mbcnt_hi_u32_b32 v216, -1, v2
	s_mov_b32 s89, s84
	s_branch .LBB0_540

; #define LAS __attribute__((address_space(3)))
; __device__ __forceinline__ void attn_phase(LAS unsigned char* lds, const bf16_t* Q, const bf16_t* Kb, const bf16_t* VT, const bf16_t* Zs, bf16_t* OZ, int vcu, int G) {
;     ...
;     for (int unit = vcu; unit < NU; unit += G) {
;         ATT_DECODE(unit, h, rowbase, q0b, kw0)
;         const int qblk = unit & 31;
;         const int qb = 8 * qblk + w, q0 = 32 * qb;
;         bf16x8 qf[4];
;         { const bf16_t* qp = Q + (rowbase + q0 + ql) * D + h * 64 + 8 * hi;
; #pragma unroll
;           for (int kk = 0; kk < 4; ++kk) qf[kk] = *(const bf16x8*)(qp + 16 * kk); }
;         u32x2 zz[8];
;         { const bf16_t* zp = Zs + (rowbase + q0 + ql) * D + h * 64 + 4 * hi;
; #pragma unroll
;           for (int g4 = 0; g4 < 4; ++g4) { zz[g4] = *(const u32x2*)(zp + 8 * g4); zz[4 + g4] = *(const u32x2*)(zp + 32 + 8 * g4); } }
;         asm volatile("" ::: "memory");
; #pragma unroll
;         for (int i = 0; i < 6; ++i) { const int idx = tid + NTHR * i, r = idx >> 3, c = idx & 7;
;             *(LAS u32x4*)(KL + r * 128 + ((c ^ ((r >> 1) & 7)) << 4)) = sk[i]; }
; #pragma unroll
;         for (int i = 0; i < 6; ++i) { const int idx = tid + NTHR * i, d = idx / 48, ch = idx % 48;
;             { u32x4 v = sv[i]; const int gp = (2 * ch) ^ (d & 31);
;                 if (d & 1) { const u32x4 t = v; v.x = t.z; v.y = t.w; v.z = t.x; v.w = t.y; }
;                 *(LAS u32x4*)(VL + d * 768 + ((gp & ~1) << 3)) = v; } }
;         __syncthreads();
;         { const int nu_ = unit + G < NU ? unit + G : unit; ATT_LOAD_STAGE(nu_); }
.LBB0_540:
	s_and_b32 s100, s84, 7
	s_bfe_u32 s99, s84, 0x20005
	s_lshl_b32 s99, s99, 3
	s_or_b32 s100, s100, s99
	s_bfe_u32 s99, s84, 0x20003
	s_lshl_b32 s99, s99, 5
	s_or_b32 s100, s100, s99
	s_bfe_u32 s99, s84, 0x20008
	s_lshl_b32 s99, s99, 7
	s_or_b32 s100, s100, s99
	s_bfe_u32 s99, s84, 0x10007
	s_lshl_b32 s99, s99, 9
	s_or_b32 s100, s100, s99
	s_ashr_i32 s74, s100, 9
	s_ashr_i32 s75, s74, 31
	s_and_b32 s58, s100, 31
	s_lshl_b64 s[78:79], s[74:75], 13
	s_lshl_b32 s74, s58, 3
	s_and_b32 s59, s100, 31
	s_lshl_b32 s81, s58, 8
	s_add_i32 s90, s74, s85
	s_lshl_b32 s91, s59, 3
	s_addk_i32 s81, 0xff80
	s_lshl_b32 s80, s90, 5
	s_add_u32 s74, s78, s80
	s_addc_u32 s75, s79, 0
	v_or_b32_e32 v190, s74, v142
	s_lshl_b32 s74, s100, 1
	s_and_b32 s92, s74, 0x3c0
	s_mov_b32 s72, s100
	s_lshl_b32 s76, s92, 1
	s_add_i32 s84, s84, s3
	s_and_b32 s101, s84, 7
	s_bfe_u32 s99, s84, 0x20005
	s_lshl_b32 s99, s99, 3
	s_or_b32 s101, s101, s99
	s_bfe_u32 s99, s84, 0x20003
	s_lshl_b32 s99, s99, 5
	s_or_b32 s101, s101, s99
	s_bfe_u32 s99, s84, 0x20008
	s_lshl_b32 s99, s99, 7
	s_or_b32 s101, s101, s99
	s_bfe_u32 s99, s84, 0x10007
	s_lshl_b32 s99, s99, 9
	s_or_b32 s101, s101, s99
	v_mov_b32_e32 v191, s75
	s_cmpk_gt_i32 s84, 0x3ff
	v_lshlrev_b64 v[2:3], 11, v[190:191]
	s_cselect_b64 s[74:75], -1, 0
	s_cmpk_lt_i32 s84, 0x400
	v_lshl_add_u64 v[4:5], s[64:65], 0, v[2:3]
	s_mov_b32 s77, s73
	v_lshl_add_u64 v[2:3], s[66:67], 0, v[2:3]
	s_cselect_b32 s72, s101, s72
	v_lshl_add_u64 v[4:5], v[4:5], 0, s[76:77]
	v_lshl_add_u64 v[2:3], v[2:3], 0, s[76:77]
	v_mov_b32_e32 v163, v145
	s_bfe_u32 s77, s72, 0x40005
	s_ashr_i32 s82, s72, 9
	s_lshl_b32 s72, s72, 8
	v_lshl_add_u64 v[4:5], v[4:5], 0, v[144:145]
	v_lshl_add_u64 v[2:3], v[2:3], 0, v[162:163]
	s_ashr_i32 s83, s82, 31
	s_and_b32 s72, s72, 0x1f00
	global_load_dwordx4 v[114:117], v[4:5], off
	global_load_dwordx4 v[118:121], v[4:5], off offset:32
	global_load_dwordx4 v[122:125], v[4:5], off offset:64
	global_load_dwordx4 v[126:129], v[4:5], off offset:96
	global_load_dwordx2 v[192:193], v[2:3], off
	global_load_dwordx2 v[186:187], v[2:3], off offset:16
	global_load_dwordx2 v[182:183], v[2:3], off offset:32
	global_load_dwordx2 v[178:179], v[2:3], off offset:48
	global_load_dwordx2 v[188:189], v[2:3], off offset:64
	global_load_dwordx2 v[184:185], v[2:3], off offset:80
	global_load_dwordx2 v[180:181], v[2:3], off offset:96
	global_load_dwordx2 v[176:177], v[2:3], off offset:112
	s_waitcnt vmcnt(17)
	v_cndmask_b32_e64 v5, v95, v97, s[48:49]
	v_cndmask_b32_e64 v4, v94, v96, s[48:49]
	v_cndmask_b32_e64 v3, v97, v95, s[48:49]
	v_cndmask_b32_e64 v2, v96, v94, s[48:49]
	s_lshl_b64 s[94:95], s[82:83], 13
	s_add_i32 s93, s72, 0xffffff80
	ds_write_b128 v206, v[66:69]
	ds_write_b128 v207, v[70:73]
	ds_write_b128 v206, v[74:77] offset:16384
	ds_write_b128 v208, v[78:81]
	ds_write_b128 v206, v[82:85] offset:32768
	ds_write_b128 v209, v[86:89]
	ds_write_b128 v210, v[2:5] offset:49152
	s_waitcnt vmcnt(16)
	v_cndmask_b32_e64 v5, v91, v93, s[4:5]
	v_cndmask_b32_e64 v4, v90, v92, s[4:5]
	v_cndmask_b32_e64 v3, v93, v91, s[4:5]
	v_cndmask_b32_e64 v2, v92, v90, s[4:5]
	s_cmp_lg_u32 s72, 0
	ds_write_b128 v211, v[2:5] offset:49152
	s_waitcnt vmcnt(15)
	v_cndmask_b32_e64 v5, v103, v105, s[6:7]
	v_cndmask_b32_e64 v4, v102, v104, s[6:7]
	v_cndmask_b32_e64 v3, v105, v103, s[6:7]
	v_cndmask_b32_e64 v2, v104, v102, s[6:7]
	s_cselect_b32 s96, s93, 0
	ds_write_b128 v212, v[2:5] offset:49152
	s_waitcnt vmcnt(14)
	v_cndmask_b32_e64 v5, v99, v101, s[8:9]
	v_cndmask_b32_e64 v4, v98, v100, s[8:9]
	v_cndmask_b32_e64 v3, v101, v99, s[8:9]
	v_cndmask_b32_e64 v2, v100, v98, s[8:9]
	s_ashr_i32 s97, s96, 31
	ds_write_b128 v213, v[2:5] offset:49152
	s_waitcnt vmcnt(13)
	v_cndmask_b32_e64 v5, v111, v113, s[10:11]
	v_cndmask_b32_e64 v4, v110, v112, s[10:11]
	v_cndmask_b32_e64 v3, v113, v111, s[10:11]
	v_cndmask_b32_e64 v2, v112, v110, s[10:11]
	s_add_u32 s94, s94, s96
	ds_write_b128 v214, v[2:5] offset:49152
	s_waitcnt vmcnt(12)
	v_cndmask_b32_e64 v5, v107, v109, s[12:13]
	v_cndmask_b32_e64 v4, v106, v108, s[12:13]
	v_cndmask_b32_e64 v3, v109, v107, s[12:13]
	v_cndmask_b32_e64 v2, v108, v106, s[12:13]
	s_addc_u32 s95, s95, s97
	ds_write_b128 v215, v[2:5] offset:49152
	s_lshl_b32 s72, s77, 7
	v_mov_b32_e32 v5, s95
	v_or_b32_e32 v4, s94, v146
	v_mov_b32_e32 v7, s95
	v_or_b32_e32 v6, s94, v148
	v_lshl_add_u64 v[2:3], v[158:159], 0, s[72:73]
	v_lshlrev_b64 v[4:5], 11, v[4:5]
	v_lshlrev_b64 v[6:7], 11, v[6:7]
	v_lshl_add_u64 v[4:5], v[2:3], 0, v[4:5]
	v_lshl_add_u64 v[6:7], v[2:3], 0, v[6:7]
	s_waitcnt lgkmcnt(0)
	s_barrier
; __device__ __forceinline__ void attn_phase(LAS unsigned char* lds, const bf16_t* Q, const bf16_t* Kb, const bf16_t* VT, const bf16_t* Zs, bf16_t* OZ, int vcu, int G) {
;     ...
;         { const int nu_ = unit + G < NU ? unit + G : unit; ATT_LOAD_STAGE(nu_); }
;         f32x16 o0, o1;
; #pragma unroll
;         for (int i = 0; i < 16; ++i) { o0[i] = 0.f; o1[i] = 0.f; }
;         float carry = 1.f;
	global_load_dwordx4 v[66:69], v[4:5], off
	global_load_dwordx4 v[70:73], v[6:7], off
	v_lshl_add_u64 v[4:5], s[94:95], 0, v[150:151]
	v_lshl_add_u64 v[6:7], s[94:95], 0, v[152:153]
	v_lshlrev_b64 v[4:5], 11, v[4:5]
	v_lshlrev_b64 v[6:7], 11, v[6:7]
	v_lshl_add_u64 v[4:5], v[2:3], 0, v[4:5]
	v_lshl_add_u64 v[6:7], v[2:3], 0, v[6:7]
	global_load_dwordx4 v[74:77], v[4:5], off
	global_load_dwordx4 v[78:81], v[6:7], off
	v_lshl_add_u64 v[4:5], s[94:95], 0, v[154:155]
	v_lshl_add_u64 v[6:7], s[94:95], 0, v[156:157]
	s_lshl_b32 s72, s77, 20
	s_lshl_b64 s[82:83], s[82:83], 14
	v_lshlrev_b64 v[4:5], 11, v[4:5]
	v_lshlrev_b64 v[6:7], 11, v[6:7]
	s_add_u32 s77, s68, s82
	v_lshl_add_u64 v[4:5], v[2:3], 0, v[4:5]
	v_lshl_add_u64 v[2:3], v[2:3], 0, v[6:7]
	s_addc_u32 s93, s69, s83
	s_lshl_b64 s[82:83], s[96:97], 1
	global_load_dwordx4 v[82:85], v[4:5], off
	global_load_dwordx4 v[86:89], v[2:3], off
	s_add_u32 s82, s77, s82
	v_or_b32_e32 v2, s72, v196
	s_addc_u32 s83, s93, s83
	v_lshlrev_b32_e32 v2, 1, v2
	v_mov_b32_e32 v3, v145
	v_or_b32_e32 v4, s72, v197
	v_lshl_add_u64 v[2:3], s[82:83], 0, v[2:3]
	v_mov_b32_e32 v165, v145
	v_lshlrev_b32_e32 v4, 1, v4
	v_mov_b32_e32 v5, v145
	v_lshl_add_u64 v[2:3], v[2:3], 0, v[164:165]
	v_lshl_add_u64 v[4:5], s[82:83], 0, v[4:5]
	v_mov_b32_e32 v167, v145
	v_lshl_add_u64 v[4:5], v[4:5], 0, v[166:167]
	global_load_dwordx4 v[94:97], v[2:3], off
	global_load_dwordx4 v[90:93], v[4:5], off
	v_or_b32_e32 v2, s72, v198
	v_lshlrev_b32_e32 v2, 1, v2
	v_mov_b32_e32 v3, v145
	v_or_b32_e32 v4, s72, v199
	v_lshl_add_u64 v[2:3], s[82:83], 0, v[2:3]
	v_mov_b32_e32 v169, v145
	v_lshlrev_b32_e32 v4, 1, v4
	v_mov_b32_e32 v5, v145
	v_lshl_add_u64 v[2:3], v[2:3], 0, v[168:169]
	v_lshl_add_u64 v[4:5], s[82:83], 0, v[4:5]
	v_mov_b32_e32 v171, v145
	v_lshl_add_u64 v[4:5], v[4:5], 0, v[170:171]
	global_load_dwordx4 v[102:105], v[2:3], off
	global_load_dwordx4 v[98:101], v[4:5], off
	v_or_b32_e32 v2, s72, v200
	v_lshlrev_b32_e32 v2, 1, v2
	v_mov_b32_e32 v3, v145
	v_or_b32_e32 v4, s72, v201
	v_lshl_add_u64 v[2:3], s[82:83], 0, v[2:3]
	v_mov_b32_e32 v173, v145
	v_lshlrev_b32_e32 v4, 1, v4
	v_mov_b32_e32 v5, v145
	v_lshl_add_u64 v[2:3], v[2:3], 0, v[172:173]
	v_lshl_add_u64 v[4:5], s[82:83], 0, v[4:5]
	v_mov_b32_e32 v175, v145
	v_lshl_add_u64 v[4:5], v[4:5], 0, v[174:175]
	global_load_dwordx4 v[110:113], v[2:3], off
	global_load_dwordx4 v[106:109], v[4:5], off
	s_cmp_lg_u32 s58, 0
	s_cselect_b32 s58, s81, 0
	s_cmp_lt_i32 s80, s58
	s_cbranch_scc1 .LBB0_552
	s_sub_i32 s72, s80, s58
	v_or_b32_e32 v2, s72, v142
	v_lshrrev_b32_e32 v27, 1, v2
	v_lshl_add_u32 v26, v2, 7, 0
	v_bitop3_b32 v2, v27, v1, 7 bitop3:0x6c
	v_lshl_add_u32 v2, v2, 4, v26
	ds_read_b128 v[2:5], v2
	s_lshr_b32 s77, s72, 2
	v_bitop3_b32 v6, s77, v142, v1 bitop3:0x36
	v_lshlrev_b32_e32 v30, 3, v6
	v_bitop3_b32 v6, v27, v143, 7 bitop3:0x6c
	v_lshl_add_u32 v6, v6, 4, v26
	ds_read_b128 v[18:21], v6
	v_or_b32_e32 v28, s77, v1
	s_waitcnt vmcnt(23) lgkmcnt(1)
	v_mfma_f32_32x32x16_bf16 v[2:17], v[2:5], v[114:117], 0
	v_bitop3_b32 v22, v28, v142, 2 bitop3:0x36
	v_lshlrev_b32_e32 v32, 3, v22
	v_bitop3_b32 v22, v28, v142, 4 bitop3:0x36
	v_lshlrev_b32_e32 v38, 3, v22
	v_bitop3_b32 v22, v27, v147, 7 bitop3:0x6c
	v_lshl_add_u32 v22, v22, 4, v26
	ds_read_b128 v[22:25], v22
	s_waitcnt vmcnt(22) lgkmcnt(1)
	v_mfma_f32_32x32x16_bf16 v[2:17], v[18:21], v[118:121], v[2:17]
	v_bitop3_b32 v18, v28, v142, 6 bitop3:0x36
	v_lshlrev_b32_e32 v39, 3, v18
	v_bitop3_b32 v18, v27, v149, 7 bitop3:0x6c
	v_lshl_add_u32 v18, v18, 4, v26
	ds_read_b128 v[26:29], v18
	v_add_u32_e32 v31, v202, v30
	v_add_u32_e32 v34, v202, v38
	s_waitcnt vmcnt(21) lgkmcnt(1)
	v_mfma_f32_32x32x16_bf16 v[2:17], v[22:25], v[122:125], v[2:17]
	v_add_u32_e32 v36, v202, v39
	v_add_u32_e32 v22, v203, v30
	v_add_u32_e32 v24, v203, v38
	v_add_u32_e32 v33, v202, v32
	ds_read_b64 v[18:19], v31 offset:49152
	ds_read_b64 v[20:21], v33 offset:49152
	ds_read_b64 v[34:35], v34 offset:49152
	ds_read_b64 v[36:37], v36 offset:49152
	v_add_u32_e32 v23, v203, v32
	v_add_u32_e32 v25, v203, v39
	s_waitcnt vmcnt(20) lgkmcnt(4)
	v_mfma_f32_32x32x16_bf16 v[2:17], v[26:29], v[126:129], v[2:17]
	ds_read_b64 v[42:43], v22 offset:24576
	ds_read_b64 v[44:45], v23 offset:24576
	ds_read_b64 v[38:39], v24 offset:24576
	ds_read_b64 v[40:41], v25 offset:24576
	v_and_b32_e32 v48, 64, v216
	v_add_u32_e32 v48, 64, v48
	s_mov_b64 s[80:81], 0
	s_nop 4
	v_min_f32_e64 v3, -v3, s98
	v_exp_f32_e32 v3, v3
	v_min_f32_e64 v4, -v4, s98
	v_exp_f32_e32 v24, v4
	v_add_f32_e32 v22, 1.0, v3
	v_min_f32_e64 v4, -v5, s98
	v_rcp_f32_e32 v22, v22
	v_exp_f32_e32 v5, v4
	v_add_f32_e32 v4, 1.0, v24
	v_mul_f32_e32 v3, v3, v22
	v_rcp_f32_e32 v25, v4
	v_cndmask_b32_e64 v4, 1.0, v3, s[16:17]
	v_add_f32_e32 v3, 1.0, v5
	v_min_f32_e64 v2, -v2, s98
	v_rcp_f32_e32 v3, v3
	v_exp_f32_e32 v2, v2
	v_mul_f32_e32 v24, v24, v25
	v_cndmask_b32_e64 v46, 1.0, v24, s[18:19]
	v_mul_f32_e32 v5, v5, v3
	v_cndmask_b32_e64 v24, 0, v3, s[20:21]
	v_min_f32_e64 v3, -v6, s98
	v_min_f32_e64 v6, -v7, s98
	v_add_f32_e32 v26, 1.0, v2
	v_exp_f32_e32 v3, v3
	v_rcp_f32_e32 v26, v26
	v_exp_f32_e32 v7, v6
	v_add_f32_e32 v6, 1.0, v3
	v_cndmask_b32_e64 v22, 0, v22, s[16:17]
	v_mul_f32_e32 v2, v2, v26
	v_cndmask_b32_e64 v23, 0, v26, s[14:15]
	v_rcp_f32_e32 v26, v6
	v_cndmask_b32_e64 v6, 1.0, v5, s[20:21]
	v_add_f32_e32 v5, 1.0, v7
	v_rcp_f32_e32 v5, v5
	v_mul_f32_e32 v3, v3, v26
	v_cndmask_b32_e64 v3, 1.0, v3, s[22:23]
	v_cndmask_b32_e64 v2, 1.0, v2, s[14:15]
	v_mul_f32_e32 v7, v7, v5
	v_cndmask_b32_e64 v27, 0, v5, s[24:25]
	v_min_f32_e64 v5, -v8, s98
	v_min_f32_e64 v8, -v9, s98
	v_exp_f32_e32 v5, v5
	v_exp_f32_e32 v8, v8
; __device__ __forceinline__ void attn_phase(LAS unsigned char* lds, const bf16_t* Q, const bf16_t* Kb, const bf16_t* VT, const bf16_t* Zs, bf16_t* OZ, int vcu, int G) {
;     ...
;         int kt = qb; bool done = false;
;     ...
;             ATT_TILE(true)
;             if (__all(carry < STOP)) { done = true; break; }
;         }
;     ...
;             ATT_TILE(false)
;             if (__all(carry < STOP)) break;
	v_cndmask_b32_e64 v28, 1.0, v7, s[24:25]
	v_add_f32_e32 v9, 1.0, v5
	v_rcp_f32_e32 v9, v9
	v_add_f32_e32 v7, 1.0, v8
	v_rcp_f32_e32 v7, v7
	v_mul_f32_e32 v3, v3, v28
	v_mul_f32_e32 v5, v5, v9
	v_cndmask_b32_e64 v30, 1.0, v5, s[26:27]
	v_mul_f32_e32 v5, v8, v7
	v_min_f32_e64 v8, -v11, s98
	v_cndmask_b32_e64 v31, 0, v7, s[28:29]
	v_min_f32_e64 v7, -v10, s98
	v_exp_f32_e32 v8, v8
	v_exp_f32_e32 v7, v7
	v_cndmask_b32_e64 v10, 1.0, v5, s[28:29]
	v_cndmask_b32_e64 v29, 0, v9, s[26:27]
	v_add_f32_e32 v5, 1.0, v8
	v_add_f32_e32 v9, 1.0, v7
	v_rcp_f32_e32 v5, v5
	v_rcp_f32_e32 v9, v9
	v_cndmask_b32_e64 v25, 0, v25, s[18:19]
	v_cndmask_b32_e64 v26, 0, v26, s[22:23]
	v_mul_f32_e32 v8, v8, v5
	v_cndmask_b32_e64 v51, 0, v5, s[34:35]
	v_min_f32_e64 v5, -v12, s98
	v_mul_f32_e32 v7, v7, v9
	v_cndmask_b32_e64 v50, 0, v9, s[30:31]
	v_min_f32_e64 v9, -v13, s98
	v_exp_f32_e32 v5, v5
	v_exp_f32_e32 v9, v9
	v_cndmask_b32_e64 v12, 1.0, v8, s[34:35]
	v_add_f32_e32 v11, 1.0, v5
	v_rcp_f32_e32 v11, v11
	v_add_f32_e32 v8, 1.0, v9
	v_rcp_f32_e32 v8, v8
	v_cndmask_b32_e64 v7, 1.0, v7, s[30:31]
	v_mul_f32_e32 v5, v5, v11
	v_cndmask_b32_e64 v52, 0, v11, s[36:37]
	v_cndmask_b32_e64 v11, 1.0, v5, s[36:37]
	v_mul_f32_e32 v5, v9, v8
	v_min_f32_e64 v9, -v15, s98
	v_exp_f32_e32 v9, v9
	v_cndmask_b32_e64 v15, 1.0, v5, s[38:39]
	v_cndmask_b32_e64 v13, 0, v8, s[38:39]
	v_min_f32_e64 v8, -v14, s98
	v_add_f32_e32 v5, 1.0, v9
	v_rcp_f32_e32 v5, v5
	v_exp_f32_e32 v8, v8
	v_mul_f32_e32 v7, v7, v12
	v_mul_f32_e32 v9, v9, v5
	v_cndmask_b32_e64 v32, 0, v5, s[42:43]
	v_min_f32_e64 v5, -v16, s98
	v_min_f32_e64 v16, -v17, s98
	v_exp_f32_e32 v5, v5
	v_exp_f32_e32 v16, v16
	v_add_f32_e32 v14, 1.0, v8
	v_add_f32_e32 v17, 1.0, v5
	v_rcp_f32_e32 v17, v17
	v_add_f32_e32 v33, 1.0, v16
	v_rcp_f32_e32 v33, v33
	v_rcp_f32_e32 v14, v14
	v_mul_f32_e32 v5, v5, v17
	v_cndmask_b32_e64 v47, 1.0, v5, s[44:45]
	v_mul_f32_e32 v5, v16, v33
	v_mul_f32_e32 v8, v8, v14
	v_cndmask_b32_e64 v16, 0, v33, s[46:47]
	v_cndmask_b32_e64 v33, 1.0, v5, s[46:47]
	v_xor_b32_e32 v5, 32, v216
	v_cndmask_b32_e64 v8, 1.0, v8, s[40:41]
	v_cndmask_b32_e64 v9, 1.0, v9, s[42:43]
	v_cmp_lt_i32_e32 vcc, v5, v48
	v_mul_f32_e32 v8, v8, v9
	v_mul_f32_e32 v48, v47, v33
	v_cndmask_b32_e32 v5, v216, v5, vcc
	v_lshlrev_b32_e32 v163, 2, v5
	v_mul_f32_e32 v8, v8, v48
	v_mov_b32_e32 v238, v8
	v_mov_b32_e32 v48, v8
	s_nop 1
	v_permlane32_swap_b32_e32 v238, v48
	s_nop 0
	v_cndmask_b32_e64 v48, v238, v48, s[0:1]
	v_mul_f32_e32 v49, v11, v15
	v_mul_f32_e32 v5, v30, v10
	v_mul_f32_e32 v7, v7, v49
	v_mul_f32_e32 v3, v3, v5
	v_mov_b32_e32 v238, v7
	v_mov_b32_e32 v53, v7
	s_nop 1
	v_permlane32_swap_b32_e32 v238, v53
	s_nop 0
	v_cndmask_b32_e64 v53, v238, v53, s[0:1]
	v_mov_b32_e32 v238, v3
	v_mov_b32_e32 v5, v3
	s_nop 1
	v_permlane32_swap_b32_e32 v238, v5
	s_nop 0
	v_cndmask_b32_e64 v5, v238, v5, s[0:1]
	s_waitcnt lgkmcnt(2)
	v_cndmask_b32_e64 v49, 1.0, v48, s[0:1]
	v_mul_f32_e32 v33, v33, v49
	v_mul_f32_e32 v47, v47, v33
	v_mul_f32_e32 v54, v9, v47
	v_mul_f32_e32 v57, v32, v47
	v_mul_f32_e32 v47, v8, v48
	s_waitcnt lgkmcnt(1)
	v_mul_f32_e32 v7, v7, v53
	v_pk_mul_f32 v[8:9], v[46:47], v[6:7]
	s_waitcnt lgkmcnt(0)
	v_pk_mul_f32 v[2:3], v[2:3], v[4:5]
	v_mul_f32_e32 v55, v16, v49
	v_pk_mul_f32 v[48:49], v[2:3], v[8:9]
	v_mov_b32_e32 v238, v48
	v_mov_b32_e32 v58, v48
	s_nop 1
	v_permlane32_swap_b32_e32 v238, v58
	s_nop 0
	v_cndmask_b32_e64 v58, v238, v58, s[0:1]
	v_mul_f32_e32 v2, v9, v5
	v_cndmask_b32_e64 v2, v9, v2, s[0:1]
	v_mul_f32_e32 v3, v10, v2
	v_mul_f32_e32 v8, v31, v2
	s_waitcnt lgkmcnt(0)
	v_mul_f32_e32 v2, v49, v58
	v_cndmask_b32_e64 v2, v49, v2, s[0:1]
	v_mul_f32_e32 v5, v30, v3
	v_mul_f32_e32 v9, v29, v3
	v_mul_f32_e32 v3, v6, v2
	v_mul_f32_e32 v6, v46, v3
	v_mul_f32_e32 v4, v4, v6
	v_mul_f32_e32 v10, v24, v2
	v_mul_f32_e32 v2, v22, v6
	v_mul_f32_e32 v6, v47, v53
	v_mul_f32_e32 v7, v28, v5
	v_cndmask_b32_e64 v6, v47, v6, s[0:1]
	v_mul_f32_e32 v5, v27, v5
	v_mul_f32_e32 v7, v26, v7
	v_mul_f32_e32 v3, v25, v3
	v_mul_f32_e32 v4, v23, v4
	v_mul_f32_e32 v47, v15, v6
	v_cndmask_b32_e64 v14, 0, v14, s[40:41]
	v_cndmask_b32_e64 v17, 0, v17, s[44:45]
	v_cvt_pk_bf16_f32 v2, v4, v2
	v_cvt_pk_bf16_f32 v3, v3, v10
	v_cvt_pk_bf16_f32 v4, v7, v5
	v_cvt_pk_bf16_f32 v5, v9, v8
	v_mul_f32_e32 v53, v11, v47
	v_mul_f32_e32 v56, v17, v33
	v_mfma_f32_32x32x16_bf16 v[18:33], v[18:21], v[2:5], 0
	v_mul_f32_e32 v46, v14, v54
	v_mul_f32_e32 v54, v12, v53
	v_mul_f32_e32 v59, v13, v6
	v_mfma_f32_32x32x16_bf16 v[2:17], v[42:45], v[2:5], 0
	v_mul_f32_e32 v43, v52, v47
	v_mul_f32_e32 v42, v51, v53
	v_mul_f32_e32 v44, v50, v54
	v_cvt_pk_bf16_f32 v42, v44, v42
	v_cvt_pk_bf16_f32 v43, v43, v59
	v_cvt_pk_bf16_f32 v44, v46, v57
	v_cvt_pk_bf16_f32 v45, v56, v55
	s_nop 1
	v_mfma_f32_32x32x16_bf16 v[18:33], v[34:37], v[42:45], v[18:33]
	v_mul_f32_e32 v34, v48, v58
	v_mul_f32_e32 v131, v34, v49
	v_cmp_gt_f32_e32 vcc, s88, v131
	s_cmp_eq_u64 vcc, exec
	v_mfma_f32_32x32x16_bf16 v[2:17], v[38:41], v[42:45], v[2:17]
	s_cbranch_scc1 .LBB0_553
	s_cmp_eq_u32 s90, 0
	s_cbranch_scc1 .LBB0_556
	s_lshl_b32 s72, s59, 8
	s_lshl_b32 s77, s59, 15
	s_sub_i32 s59, s72, 32
	v_add_u32_e32 v34, s72, v204
	s_lshl_b32 s72, s58, 7
	s_sub_i32 s72, s77, s72
	s_add_i32 s93, s86, s91
	v_subrev_u32_e32 v165, s58, v34
	v_add_u32_e32 v167, s72, v205
	s_sub_i32 s77, s59, s58
	s_nop 7
	v_mov_b64_e32 v[34:35], v[2:3]
	v_mov_b64_e32 v[36:37], v[4:5]
	v_mov_b64_e32 v[38:39], v[6:7]
	v_mov_b64_e32 v[40:41], v[8:9]
	v_mov_b64_e32 v[42:43], v[10:11]
	v_mov_b64_e32 v[44:45], v[12:13]
	v_mov_b64_e32 v[46:47], v[14:15]
	v_mov_b64_e32 v[48:49], v[16:17]
	v_mov_b64_e32 v[50:51], v[18:19]
	v_mov_b64_e32 v[52:53], v[20:21]
	v_mov_b64_e32 v[54:55], v[22:23]
	v_mov_b64_e32 v[56:57], v[24:25]
	v_mov_b64_e32 v[58:59], v[26:27]
	v_mov_b64_e32 v[60:61], v[28:29]
	v_mov_b64_e32 v[62:63], v[30:31]
	v_mov_b64_e32 v[64:65], v[32:33]
	s_branch .LBB0_545
